# attention: static s_setprio 1 for waves 4-7 during the attention phase (desynchronise the SIMD wave pair)
# speedup vs baseline: 1.0004x; 1.0004x over previous
.LBB0_254:
	v_writelane_b32 v254, s56, 63
	v_readfirstlane_b32 s2, v154
	s_nop 3
	s_cmpk_ge_u32 s2, 0x100
	s_cbranch_scc0 .Lattn_prio_skip
	s_setprio 1
.Lattn_prio_skip:
	v_readlane_b32 s0, v254, 58
	v_readlane_b32 s1, v254, 59
	s_and_b64 s[0:1], s[0:1], exec
	s_movk_i32 s0, 0x618
	s_cselect_b32 s6, s0, 0x600
	s_cmp_ge_i32 s84, s6
	v_writelane_b32 v252, s57, 0
	s_cbranch_scc1 .LBB0_352
	v_or_b32_e32 v3, v38, v37
	v_bfe_u32 v5, v154, 1, 1
	v_lshrrev_b32_e32 v4, 1, v154
	v_or_b32_e32 v10, v3, v5
	v_lshlrev_b32_e32 v163, 4, v10
	v_bitop3_b32 v10, v3, v4, 1 bitop3:0x72
	v_lshlrev_b32_e32 v164, 4, v10
	v_or_b32_e32 v10, 2, v5
	v_bitop3_b32 v11, v38, v10, v37 bitop3:0x36
	v_bitop3_b32 v10, v3, v10, 1 bitop3:0x36
	v_lshlrev_b32_e32 v166, 4, v10
	v_or_b32_e32 v10, 4, v5
	v_lshlrev_b32_e32 v165, 4, v11
	v_bitop3_b32 v11, v38, v10, v37 bitop3:0x36
	v_bitop3_b32 v10, v3, v10, 1 bitop3:0x36
	v_lshlrev_b32_e32 v168, 4, v10
	v_or_b32_e32 v10, 6, v5
	v_lshlrev_b32_e32 v2, 1, v140
	v_lshlrev_b32_e32 v167, 4, v11
	v_bitop3_b32 v11, v38, v10, v37 bitop3:0x36
	v_bitop3_b32 v10, v3, v10, 1 bitop3:0x36
	v_lshrrev_b32_e32 v0, 4, v154
	v_and_or_b32 v2, v2, 24, v39
	v_lshlrev_b32_e32 v170, 4, v10
	v_or_b32_e32 v10, 8, v5
	v_bfe_u32 v148, v154, 4, 2
	v_lshlrev_b32_e32 v149, 8, v2
	v_bitop3_b32 v2, v0, v140, 3 bitop3:0x6c
	v_readlane_b32 s0, v254, 58
	v_lshlrev_b32_e32 v169, 4, v11
	v_bitop3_b32 v11, v38, v10, v37 bitop3:0x36
	v_bitop3_b32 v10, v3, v10, 1 bitop3:0x36
	v_lshlrev_b32_e32 v150, 4, v2
	v_bitop3_b32 v2, v148, v140, 4 bitop3:0x36
	v_readlane_b32 s1, v254, 59
	v_lshlrev_b32_e32 v172, 4, v10
	v_or_b32_e32 v10, 10, v5
	v_lshlrev_b32_e32 v152, 4, v2
	v_bitop3_b32 v2, v148, v140, 8 bitop3:0x36
	s_and_b64 s[0:1], s[0:1], exec
	v_lshlrev_b32_e32 v171, 4, v11
	v_bitop3_b32 v11, v38, v10, v37 bitop3:0x36
	v_bitop3_b32 v10, v3, v10, 1 bitop3:0x36
	v_lshlrev_b32_e32 v156, 4, v2
	v_bitop3_b32 v2, v148, v140, 12 bitop3:0x36
	s_cselect_b32 s7, 0, 8
	s_cselect_b32 s29, 0, 4
	v_lshlrev_b32_e32 v174, 4, v10
	v_or_b32_e32 v10, 12, v5
	v_or_b32_e32 v5, 14, v5
	v_bfe_u32 v13, v0, 1, 1
	v_bitop3_b32 v0, v0, v154, 3 bitop3:0x6c
	s_ashr_i32 s3, s2, 6
	v_max_i32_e32 v29, 0xffffffd1, v154
	v_lshlrev_b32_e32 v158, 4, v2
	v_lshlrev_b32_e32 v2, 6, v140
	v_lshrrev_b32_e32 v6, 1, v142
	v_lshrrev_b32_e32 v9, 1, v143
	v_lshlrev_b32_e32 v173, 4, v11
	v_bitop3_b32 v11, v38, v10, v37 bitop3:0x36
	v_bitop3_b32 v10, v3, v10, 1 bitop3:0x36
	v_bitop3_b32 v3, v3, v5, 1 bitop3:0x36
	v_lshlrev_b32_e32 v0, 4, v0
	s_lshl_b32 s18, s3, 5
	s_ashr_i32 s31, s2, 7
	s_lshl_b32 s2, s3, 13
	v_sub_u32_e32 v29, v29, v154
	v_and_b32_e32 v2, 0x300, v2
	v_and_b32_e32 v6, 12, v6
	v_bfe_u32 v8, v155, 4, 2
	v_and_b32_e32 v9, 12, v9
	v_lshlrev_b32_e32 v176, 4, v10
	v_bitop3_b32 v10, v38, v5, v37 bitop3:0x36
	v_lshlrev_b32_e32 v178, 4, v3
	v_lshl_add_u32 v3, v148, 11, 0
	v_and_b32_e32 v21, 0xf0, v0
	s_add_i32 s30, s18, 0x8000
	s_and_b32 s52, s18, 32
	v_lshlrev_b32_e32 v0, 4, v148
	s_add_i32 s2, s2, 0
	v_readlane_b32 s18, v254, 56
	v_add_u32_e32 v29, 0x1ff, v29
	v_or_b32_e32 v151, 4, v148
	v_or_b32_e32 v153, 8, v148
	v_or_b32_e32 v157, 12, v148
	v_bitop3_b32 v6, v6, v140, v148 bitop3:0x36
	v_bitop3_b32 v8, v9, v140, v8 bitop3:0x36
	v_lshlrev_b32_e32 v175, 4, v11
	v_lshlrev_b32_e32 v177, 4, v10
	v_or_b32_e32 v179, 16, v148
	v_or_b32_e32 v180, 20, v148
	v_or_b32_e32 v181, 24, v148
	v_or_b32_e32 v182, 28, v148
	v_add3_u32 v183, v3, v2, v36
	v_bitop3_b32 v2, v148, v154, 28 bitop3:0x36
	v_bitop3_b32 v3, v148, v154, 24 bitop3:0x36
	v_bitop3_b32 v5, v148, v154, 20 bitop3:0x36
	v_bitop3_b32 v10, v148, v154, 12 bitop3:0x36
	v_bitop3_b32 v11, v148, v154, 8 bitop3:0x36
	v_bitop3_b32 v12, v148, v154, 4 bitop3:0x36
	v_and_b32_e32 v4, 8, v4
	v_lshlrev_b32_e32 v22, 8, v140
	v_lshl_add_u64 v[132:133], s[16:17], 0, v[0:1]
	s_add_i32 s2, s2, 0x11200
	v_lshlrev_b32_e32 v0, 4, v140
	v_readlane_b32 s19, v254, 57
	v_lshrrev_b32_e32 v30, 9, v29
	v_lshlrev_b32_e32 v160, 4, v6
	v_lshlrev_b32_e32 v161, 4, v8
	v_lshlrev_b32_e32 v2, 4, v2
	v_lshlrev_b32_e32 v3, 4, v3
	v_lshlrev_b32_e32 v5, 4, v5
	v_lshlrev_b32_e32 v10, 4, v10
	v_lshlrev_b32_e32 v11, 4, v11
	v_lshlrev_b32_e32 v12, 4, v12
	v_bitop3_b32 v14, v13, v140, 14 bitop3:0x36
	v_bitop3_b32 v15, v13, v140, 12 bitop3:0x36
	v_bitop3_b32 v16, v13, v140, 10 bitop3:0x36
	v_bitop3_b32 v17, v13, v140, 8 bitop3:0x36
	v_bitop3_b32 v18, v13, v140, 6 bitop3:0x36
	v_bitop3_b32 v19, v13, v140, 4 bitop3:0x36
	v_bitop3_b32 v20, v13, v140, 2 bitop3:0x36
	v_xor_b32_e32 v13, v13, v140
	v_add3_u32 v4, s2, v22, v4
	v_lshl_add_u64 v[134:135], s[18:19], 0, v[0:1]
	v_lshl_add_u32 v22, v148, 8, s2
	v_lshl_add_u64 v[136:137], s[16:17], 0, v[0:1]
	v_lshl_add_u32 v0, v151, 8, s2
	v_lshl_add_u32 v23, v153, 8, s2
	v_lshl_add_u32 v24, v157, 8, s2
	v_lshl_add_u32 v25, v179, 8, s2
	v_lshl_add_u32 v26, v180, 8, s2
	v_lshl_add_u32 v27, v181, 8, s2
	v_lshl_add_u32 v28, v182, 8, s2
	v_add_u32_e32 v30, 1, v30
	s_movk_i32 s2, 0x1ff
	s_movk_i32 s0, 0x1d0
	v_lshlrev_b32_e32 v159, 3, v148
	v_add_u32_e32 v6, 0, v160
	v_add_u32_e32 v7, 0, v145
	v_add_u32_e32 v8, 0, v161
	v_add_u32_e32 v9, 0, v147
	v_and_b32_e32 v2, 0xf0, v2
	v_and_b32_e32 v3, 0xf0, v3
	v_and_b32_e32 v5, 0xf0, v5
	v_and_b32_e32 v10, 0xf0, v10
	v_and_b32_e32 v11, 0xf0, v11
	v_and_b32_e32 v12, 0xf0, v12
	v_lshlrev_b32_e32 v14, 4, v14
	v_lshlrev_b32_e32 v15, 4, v15
	v_lshlrev_b32_e32 v16, 4, v16
	v_lshlrev_b32_e32 v17, 4, v17
	v_lshlrev_b32_e32 v18, 4, v18
	v_lshlrev_b32_e32 v19, 4, v19
	v_lshlrev_b32_e32 v20, 4, v20
	v_lshlrev_b32_e32 v13, 4, v13
	v_cmp_lt_u32_e64 s[36:37], s2, v29
	v_and_b32_e32 v184, 0xfffffe, v30
	v_readlane_b32 s2, v253, 48
	v_cmp_lt_i32_e64 s[0:1], s0, v154
	v_or_b32_e32 v162, 0x80, v159
	v_lshl_add_u32 v185, v184, 9, v154
	v_cmp_ne_u32_e64 s[38:39], v30, v184
	v_add_u32_e32 v186, s2, v141
	v_add_u32_e32 v187, v6, v144
	v_add_u32_e32 v188, v7, v144
	v_add_u32_e32 v189, v8, v146
	v_add_u32_e32 v190, v9, v146
	v_add_u32_e32 v191, v4, v13
	v_add_u32_e32 v192, v4, v20
	v_add_u32_e32 v193, v4, v19
	v_add_u32_e32 v194, v4, v18
	v_add_u32_e32 v195, v4, v17
	v_add_u32_e32 v196, v4, v16
	v_add_u32_e32 v197, v4, v15
	v_add_u32_e32 v198, v4, v14
	v_add_u32_e32 v199, v22, v21
	v_add_u32_e32 v200, v0, v12
	v_add_u32_e32 v201, v23, v11
	v_add_u32_e32 v202, v24, v10
	v_add_u32_e32 v203, v25, v21
	v_add_u32_e32 v204, v26, v5
	v_add_u32_e32 v205, v27, v3
	v_add_u32_e32 v223, v28, v2
	s_mov_b32 s53, s84
	s_mov_b32 s96, s94
	s_branch .LBB0_258

.LBB0_352:
	s_setprio 0
	v_readlane_b32 s48, v254, 46
	v_readlane_b32 s38, v254, 58
	v_readlane_b32 s56, v254, 63
	s_mov_b64 s[0:1], 0
	v_readlane_b32 s49, v254, 47
	s_movk_i32 s52, 0x1000
	s_mov_b32 s51, 0x2aaaaaab
	s_movk_i32 s53, 0x1800
	v_readlane_b32 s39, v254, 59
	v_readlane_b32 s78, v254, 14
	v_readlane_b32 s57, v252, 0
